# dn_prep forward substitution on the f32 matrix core: rows solved in blocks of four, each earlier row k applied with one v_mfma_f32_4x4x1_16b_f32 (f32 operands, f32 accumulate, k-ascending fma chain) i
# speedup vs baseline: 1.0095x; 1.0085x over previous
; #define LAS __attribute__((address_space(3)))
; __device__ __forceinline__ float bf2f(unsigned short v) { return __uint_as_float(((unsigned)v) << 16); }
; __device__ __forceinline__ void dn_prep_item(const Args& a, LAS unsigned char* lds, int item, int tid, int wave, int lane, int& cwh, int next_item) {
;     ...
;     if (wave < 4) {
;         float x[64];
;         { const LAS unsigned char* src = lds + (tid < 128 ? L_V : L_KH) + 2 * (tid & 127); const LAS float* fac = tid < 128 ? betas : bks;
; #pragma unroll
;           for (int i = 0; i < 64; ++i) x[i] = bf2f(*(const LAS unsigned short*)(src + i * KS_)) * fac[i]; }
.LBB0_878:
	s_and_b64 vcc, exec, s[22:23]
	s_cbranch_vccz .LBB0_880
	v_and_b32_e32 v234, 3, v206
	v_mul_u32_u24_e32 v234, 0x110, v234
	v_add_u32_e32 v234, 0x8800, v234
	ds_read_b128 v[88:91], v190
	ds_read_b128 v[92:95], v191
	ds_read_b128 v[96:99], v192
	ds_read_b128 v[100:103], v193
	ds_read_u16 v0, v189
	ds_read_u16 v1, v189 offset:272
	ds_read_u16 v2, v189 offset:544
	ds_read_u16 v3, v189 offset:816
	ds_read_u16 v4, v189 offset:1088
	ds_read_u16 v5, v189 offset:1360
	ds_read_u16 v6, v189 offset:1632
	ds_read_u16 v7, v189 offset:1904
	ds_read_u16 v8, v189 offset:2176
	ds_read_u16 v9, v189 offset:2448
	ds_read_u16 v10, v189 offset:2720
	ds_read_u16 v11, v189 offset:2992
	ds_read_u16 v12, v189 offset:3264
	ds_read_u16 v13, v189 offset:3536
	ds_read_u16 v14, v189 offset:3808
	ds_read_u16 v15, v189 offset:4080
	s_waitcnt lgkmcnt(0)
	v_lshlrev_b32_e32 v0, 16, v0
	v_lshlrev_b32_e32 v1, 16, v1
	v_lshlrev_b32_e32 v2, 16, v2
	v_lshlrev_b32_e32 v3, 16, v3
	v_lshlrev_b32_e32 v4, 16, v4
	v_lshlrev_b32_e32 v5, 16, v5
	v_lshlrev_b32_e32 v6, 16, v6
	v_lshlrev_b32_e32 v7, 16, v7
	v_lshlrev_b32_e32 v8, 16, v8
	v_lshlrev_b32_e32 v9, 16, v9
	v_lshlrev_b32_e32 v10, 16, v10
	v_lshlrev_b32_e32 v11, 16, v11
	v_lshlrev_b32_e32 v12, 16, v12
	v_lshlrev_b32_e32 v13, 16, v13
	v_lshlrev_b32_e32 v14, 16, v14
	v_lshlrev_b32_e32 v15, 16, v15
	v_mul_f32_e32 v0, v88, v0
	v_mul_f32_e32 v1, v89, v1
	v_mul_f32_e32 v2, v90, v2
	v_mul_f32_e32 v3, v91, v3
	v_mul_f32_e32 v4, v92, v4
	v_mul_f32_e32 v5, v93, v5
	v_mul_f32_e32 v6, v94, v6
	v_mul_f32_e32 v7, v95, v7
	v_mul_f32_e32 v8, v96, v8
	v_mul_f32_e32 v9, v97, v9
	v_mul_f32_e32 v10, v98, v10
	v_mul_f32_e32 v11, v99, v11
	v_mul_f32_e32 v12, v100, v12
	v_mul_f32_e32 v13, v101, v13
	v_mul_f32_e32 v14, v102, v14
	v_mul_f32_e32 v15, v103, v15
	ds_read_b128 v[88:91], v194
	ds_read_b128 v[92:95], v195
	ds_read_b128 v[96:99], v196
	ds_read_b128 v[100:103], v197
	ds_read_u16 v16, v189 offset:4352
	ds_read_u16 v17, v189 offset:4624
	ds_read_u16 v18, v189 offset:4896
	ds_read_u16 v19, v189 offset:5168
	ds_read_u16 v20, v189 offset:5440
	ds_read_u16 v21, v189 offset:5712
	ds_read_u16 v22, v189 offset:5984
	ds_read_u16 v23, v189 offset:6256
	ds_read_u16 v24, v189 offset:6528
	ds_read_u16 v25, v189 offset:6800
	ds_read_u16 v26, v189 offset:7072
	ds_read_u16 v27, v189 offset:7344
	ds_read_u16 v28, v189 offset:7616
	ds_read_u16 v29, v189 offset:7888
	ds_read_u16 v30, v189 offset:8160
	ds_read_u16 v31, v189 offset:8432
	s_waitcnt lgkmcnt(0)
	v_lshlrev_b32_e32 v16, 16, v16
	v_lshlrev_b32_e32 v17, 16, v17
	v_lshlrev_b32_e32 v18, 16, v18
	v_lshlrev_b32_e32 v19, 16, v19
	v_lshlrev_b32_e32 v20, 16, v20
	v_lshlrev_b32_e32 v21, 16, v21
	v_lshlrev_b32_e32 v22, 16, v22
	v_lshlrev_b32_e32 v23, 16, v23
	v_lshlrev_b32_e32 v24, 16, v24
	v_lshlrev_b32_e32 v25, 16, v25
	v_lshlrev_b32_e32 v26, 16, v26
	v_lshlrev_b32_e32 v27, 16, v27
	v_lshlrev_b32_e32 v28, 16, v28
	v_lshlrev_b32_e32 v29, 16, v29
	v_lshlrev_b32_e32 v30, 16, v30
	v_lshlrev_b32_e32 v31, 16, v31
	v_mul_f32_e32 v16, v88, v16
	v_mul_f32_e32 v17, v89, v17
	v_mul_f32_e32 v18, v90, v18
	v_mul_f32_e32 v19, v91, v19
	v_mul_f32_e32 v20, v92, v20
	v_mul_f32_e32 v21, v93, v21
	v_mul_f32_e32 v22, v94, v22
	v_mul_f32_e32 v23, v95, v23
	v_mul_f32_e32 v24, v96, v24
	v_mul_f32_e32 v25, v97, v25
	v_mul_f32_e32 v26, v98, v26
	v_mul_f32_e32 v27, v99, v27
	v_mul_f32_e32 v28, v100, v28
	v_mul_f32_e32 v29, v101, v29
	v_mul_f32_e32 v30, v102, v30
	v_mul_f32_e32 v31, v103, v31
	ds_read_b128 v[88:91], v198
	ds_read_b128 v[92:95], v199
	ds_read_b128 v[96:99], v201
	ds_read_b128 v[100:103], v202
	ds_read_u16 v32, v189 offset:8704
	ds_read_u16 v33, v189 offset:8976
	ds_read_u16 v34, v189 offset:9248
	ds_read_u16 v35, v189 offset:9520
	ds_read_u16 v36, v189 offset:9792
	ds_read_u16 v37, v189 offset:10064
	ds_read_u16 v38, v189 offset:10336
	ds_read_u16 v39, v189 offset:10608
	ds_read_u16 v40, v189 offset:10880
	ds_read_u16 v41, v189 offset:11152
	ds_read_u16 v42, v189 offset:11424
	ds_read_u16 v43, v189 offset:11696
	ds_read_u16 v44, v189 offset:11968
	ds_read_u16 v45, v189 offset:12240
	ds_read_u16 v46, v189 offset:12512
	ds_read_u16 v47, v189 offset:12784
	s_waitcnt lgkmcnt(0)
	v_lshlrev_b32_e32 v32, 16, v32
	v_lshlrev_b32_e32 v33, 16, v33
	v_lshlrev_b32_e32 v34, 16, v34
	v_lshlrev_b32_e32 v35, 16, v35
	v_lshlrev_b32_e32 v36, 16, v36
	v_lshlrev_b32_e32 v37, 16, v37
	v_lshlrev_b32_e32 v38, 16, v38
	v_lshlrev_b32_e32 v39, 16, v39
	v_lshlrev_b32_e32 v40, 16, v40
	v_lshlrev_b32_e32 v41, 16, v41
	v_lshlrev_b32_e32 v42, 16, v42
	v_lshlrev_b32_e32 v43, 16, v43
	v_lshlrev_b32_e32 v44, 16, v44
	v_lshlrev_b32_e32 v45, 16, v45
	v_lshlrev_b32_e32 v46, 16, v46
	v_lshlrev_b32_e32 v47, 16, v47
	v_mul_f32_e32 v32, v88, v32
	v_mul_f32_e32 v33, v89, v33
	v_mul_f32_e32 v34, v90, v34
	v_mul_f32_e32 v35, v91, v35
	v_mul_f32_e32 v36, v92, v36
	v_mul_f32_e32 v37, v93, v37
	v_mul_f32_e32 v38, v94, v38
	v_mul_f32_e32 v39, v95, v39
	v_mul_f32_e32 v40, v96, v40
	v_mul_f32_e32 v41, v97, v41
	v_mul_f32_e32 v42, v98, v42
	v_mul_f32_e32 v43, v99, v43
	v_mul_f32_e32 v44, v100, v44
	v_mul_f32_e32 v45, v101, v45
	v_mul_f32_e32 v46, v102, v46
	v_mul_f32_e32 v47, v103, v47
	ds_read_b128 v[88:91], v203
	ds_read_b128 v[92:95], v204
	ds_read_b128 v[96:99], v205
	ds_read_b128 v[100:103], v207
	ds_read_u16 v72, v189 offset:13056
	ds_read_u16 v73, v189 offset:13328
	ds_read_u16 v74, v189 offset:13600
	ds_read_u16 v75, v189 offset:13872
	ds_read_u16 v76, v189 offset:14144
	ds_read_u16 v77, v189 offset:14416
	ds_read_u16 v78, v189 offset:14688
	ds_read_u16 v79, v189 offset:14960
	ds_read_u16 v80, v189 offset:15232
	ds_read_u16 v81, v189 offset:15504
	ds_read_u16 v82, v189 offset:15776
	ds_read_u16 v83, v189 offset:16048
	ds_read_u16 v84, v189 offset:16320
	ds_read_u16 v85, v189 offset:16592
	ds_read_u16 v86, v189 offset:16864
	ds_read_u16 v87, v189 offset:17136
	s_waitcnt lgkmcnt(0)
; #define LAS __attribute__((address_space(3)))
; __device__ __forceinline__ float bf2f(unsigned short v) { return __uint_as_float(((unsigned)v) << 16); }
; __device__ __forceinline__ void dn_prep_item(const Args& a, LAS unsigned char* lds, int item, int tid, int wave, int lane, int& cwh, int next_item) {
;     ...
;           for (int i = 0; i < 64; ++i) x[i] = bf2f(*(const LAS unsigned short*)(src + i * KS_)) * fac[i]; }
;         { const LAS float* lrow = Lm + (lane & 15);
; #pragma unroll
;         for (int i = 1; i < 64; ++i) { float sa[4] = { x[i], 0.f, 0.f, 0.f };
;             int lr[4];
; #pragma unroll
;             for (int g = 0; g < (i + 15) / 16; ++g) lr[g] = __float_as_int(lrow[i * 68 + 16 * g]);
; #pragma unroll
;             for (int j = 0; j < i; ++j) { fmac_rowbcast_sel(sa[j & 3], lr[j >> 4], x[j], j); }
;             x[i] = (sa[0] + sa[1]) + (sa[2] + sa[3]); } }
	v_lshlrev_b32_e32 v72, 16, v72
	v_lshlrev_b32_e32 v73, 16, v73
	v_lshlrev_b32_e32 v74, 16, v74
	v_lshlrev_b32_e32 v75, 16, v75
	v_lshlrev_b32_e32 v76, 16, v76
	v_lshlrev_b32_e32 v77, 16, v77
	v_lshlrev_b32_e32 v78, 16, v78
	v_lshlrev_b32_e32 v79, 16, v79
	v_lshlrev_b32_e32 v80, 16, v80
	v_lshlrev_b32_e32 v81, 16, v81
	v_lshlrev_b32_e32 v82, 16, v82
	v_lshlrev_b32_e32 v83, 16, v83
	v_lshlrev_b32_e32 v84, 16, v84
	v_lshlrev_b32_e32 v85, 16, v85
	v_lshlrev_b32_e32 v86, 16, v86
	v_lshlrev_b32_e32 v87, 16, v87
	v_mul_f32_e32 v72, v88, v72
	v_mul_f32_e32 v73, v89, v73
	v_mul_f32_e32 v74, v90, v74
	v_mul_f32_e32 v75, v91, v75
	v_mul_f32_e32 v76, v92, v76
	v_mul_f32_e32 v77, v93, v77
	v_mul_f32_e32 v78, v94, v78
	v_mul_f32_e32 v79, v95, v79
	v_mul_f32_e32 v80, v96, v80
	v_mul_f32_e32 v81, v97, v81
	v_mul_f32_e32 v82, v98, v82
	v_mul_f32_e32 v83, v99, v83
	v_mul_f32_e32 v84, v100, v84
	v_mul_f32_e32 v85, v101, v85
	v_mul_f32_e32 v86, v102, v86
	v_mul_f32_e32 v87, v103, v87
	ds_read_b128 v[88:91], v234 offset:0
	ds_read_b128 v[104:107], v234 offset:1088
	ds_read_b128 v[108:111], v234 offset:1104
	ds_read_b128 v[120:123], v234 offset:2176
	ds_read_b128 v[124:127], v234 offset:2192
	ds_read_b128 v[128:131], v234 offset:2208
	s_waitcnt lgkmcnt(5)
	s_nop 4
	s_nop 3
	v_mov_b32_e32 v235, v0
	s_nop 1
	v_mfma_f32_4x4x1_16b_f32 v[0:3], v88, v235, v[0:3]
	s_nop 1
	s_nop 3
	v_mov_b32_e32 v235, v1
	s_nop 1
	v_mfma_f32_4x4x1_16b_f32 v[0:3], v89, v235, v[0:3]
	s_nop 1
	s_nop 3
	v_mov_b32_e32 v235, v2
	s_nop 1
	v_mfma_f32_4x4x1_16b_f32 v[0:3], v90, v235, v[0:3]
	s_nop 1
	ds_read_b128 v[88:91], v234 offset:3264
	ds_read_b128 v[92:95], v234 offset:3280
	ds_read_b128 v[96:99], v234 offset:3296
	ds_read_b128 v[100:103], v234 offset:3312
	s_waitcnt lgkmcnt(7)
	s_nop 4
	v_mfma_f32_4x4x1_16b_f32 v[4:7], v104, v0, v[4:7]
	s_nop 1
	v_mfma_f32_4x4x1_16b_f32 v[4:7], v105, v1, v[4:7]
	s_nop 1
	v_mfma_f32_4x4x1_16b_f32 v[4:7], v106, v2, v[4:7]
	s_nop 1
	v_mfma_f32_4x4x1_16b_f32 v[4:7], v107, v3, v[4:7]
	s_nop 1
	s_nop 3
	v_mov_b32_e32 v235, v4
	s_nop 1
	v_mfma_f32_4x4x1_16b_f32 v[4:7], v108, v235, v[4:7]
	s_nop 1
	s_nop 3
	v_mov_b32_e32 v235, v5
	s_nop 1
	v_mfma_f32_4x4x1_16b_f32 v[4:7], v109, v235, v[4:7]
	s_nop 1
	s_nop 3
	v_mov_b32_e32 v235, v6
	s_nop 1
	v_mfma_f32_4x4x1_16b_f32 v[4:7], v110, v235, v[4:7]
	s_nop 1
	ds_read_b128 v[104:107], v234 offset:4352
	ds_read_b128 v[108:111], v234 offset:4368
	ds_read_b128 v[112:115], v234 offset:4384
	ds_read_b128 v[116:119], v234 offset:4400
	s_waitcnt lgkmcnt(8)
	s_nop 4
	v_mfma_f32_4x4x1_16b_f32 v[8:11], v120, v0, v[8:11]
	s_nop 1
	v_mfma_f32_4x4x1_16b_f32 v[8:11], v121, v1, v[8:11]
	s_nop 1
	v_mfma_f32_4x4x1_16b_f32 v[8:11], v122, v2, v[8:11]
	s_nop 1
	v_mfma_f32_4x4x1_16b_f32 v[8:11], v123, v3, v[8:11]
	s_nop 1
	v_mfma_f32_4x4x1_16b_f32 v[8:11], v124, v4, v[8:11]
	s_nop 1
	v_mfma_f32_4x4x1_16b_f32 v[8:11], v125, v5, v[8:11]
	s_nop 1
	v_mfma_f32_4x4x1_16b_f32 v[8:11], v126, v6, v[8:11]
	s_nop 1
	v_mfma_f32_4x4x1_16b_f32 v[8:11], v127, v7, v[8:11]
	s_nop 1
	s_nop 3
	v_mov_b32_e32 v235, v8
	s_nop 1
	v_mfma_f32_4x4x1_16b_f32 v[8:11], v128, v235, v[8:11]
	s_nop 1
	s_nop 3
	v_mov_b32_e32 v235, v9
	s_nop 1
	v_mfma_f32_4x4x1_16b_f32 v[8:11], v129, v235, v[8:11]
	s_nop 1
	s_nop 3
	v_mov_b32_e32 v235, v10
	s_nop 1
	v_mfma_f32_4x4x1_16b_f32 v[8:11], v130, v235, v[8:11]
	s_nop 1
	ds_read_b128 v[120:123], v234 offset:4416
	s_waitcnt lgkmcnt(5)
	s_nop 4
	v_mfma_f32_4x4x1_16b_f32 v[12:15], v88, v0, v[12:15]
	s_nop 1
	v_mfma_f32_4x4x1_16b_f32 v[12:15], v89, v1, v[12:15]
	s_nop 1
	v_mfma_f32_4x4x1_16b_f32 v[12:15], v90, v2, v[12:15]
	s_nop 1
	v_mfma_f32_4x4x1_16b_f32 v[12:15], v91, v3, v[12:15]
	s_nop 1
	v_mfma_f32_4x4x1_16b_f32 v[12:15], v92, v4, v[12:15]
	s_nop 1
	v_mfma_f32_4x4x1_16b_f32 v[12:15], v93, v5, v[12:15]
	s_nop 1
	v_mfma_f32_4x4x1_16b_f32 v[12:15], v94, v6, v[12:15]
	s_nop 1
	v_mfma_f32_4x4x1_16b_f32 v[12:15], v95, v7, v[12:15]
	s_nop 1
	v_mfma_f32_4x4x1_16b_f32 v[12:15], v96, v8, v[12:15]
	s_nop 1
	v_mfma_f32_4x4x1_16b_f32 v[12:15], v97, v9, v[12:15]
	s_nop 1
	v_mfma_f32_4x4x1_16b_f32 v[12:15], v98, v10, v[12:15]
	s_nop 1
	v_mfma_f32_4x4x1_16b_f32 v[12:15], v99, v11, v[12:15]
	s_nop 1
	s_nop 3
	v_mov_b32_e32 v235, v12
	s_nop 1
	v_mfma_f32_4x4x1_16b_f32 v[12:15], v100, v235, v[12:15]
	s_nop 1
	s_nop 3
	v_mov_b32_e32 v235, v13
	s_nop 1
	v_mfma_f32_4x4x1_16b_f32 v[12:15], v101, v235, v[12:15]
	s_nop 1
	s_nop 3
	v_mov_b32_e32 v235, v14
	s_nop 1
	v_mfma_f32_4x4x1_16b_f32 v[12:15], v102, v235, v[12:15]
	s_nop 1
	ds_read_b128 v[88:91], v234 offset:5440
	ds_read_b128 v[92:95], v234 offset:5456
	ds_read_b128 v[96:99], v234 offset:5472
	ds_read_b128 v[100:103], v234 offset:5488
	s_waitcnt lgkmcnt(5)
	s_nop 4
	v_mfma_f32_4x4x1_16b_f32 v[16:19], v104, v0, v[16:19]
	s_nop 1
	v_mfma_f32_4x4x1_16b_f32 v[16:19], v105, v1, v[16:19]
	s_nop 1
	v_mfma_f32_4x4x1_16b_f32 v[16:19], v106, v2, v[16:19]
	s_nop 1
	v_mfma_f32_4x4x1_16b_f32 v[16:19], v107, v3, v[16:19]
	s_nop 1
	v_mfma_f32_4x4x1_16b_f32 v[16:19], v108, v4, v[16:19]
	s_nop 1
	v_mfma_f32_4x4x1_16b_f32 v[16:19], v109, v5, v[16:19]
	s_nop 1
	v_mfma_f32_4x4x1_16b_f32 v[16:19], v110, v6, v[16:19]
	s_nop 1
	v_mfma_f32_4x4x1_16b_f32 v[16:19], v111, v7, v[16:19]
	s_nop 1
	v_mfma_f32_4x4x1_16b_f32 v[16:19], v112, v8, v[16:19]
	s_nop 1
	v_mfma_f32_4x4x1_16b_f32 v[16:19], v113, v9, v[16:19]
	s_nop 1
	v_mfma_f32_4x4x1_16b_f32 v[16:19], v114, v10, v[16:19]
	s_nop 1
	v_mfma_f32_4x4x1_16b_f32 v[16:19], v115, v11, v[16:19]
	s_nop 1
	v_mfma_f32_4x4x1_16b_f32 v[16:19], v116, v12, v[16:19]
	s_nop 1
	v_mfma_f32_4x4x1_16b_f32 v[16:19], v117, v13, v[16:19]
	s_nop 1
	v_mfma_f32_4x4x1_16b_f32 v[16:19], v118, v14, v[16:19]
	s_nop 1
	v_mfma_f32_4x4x1_16b_f32 v[16:19], v119, v15, v[16:19]
	s_nop 1
	ds_read_b128 v[104:107], v234 offset:5504
	ds_read_b128 v[108:111], v234 offset:5520
	s_waitcnt lgkmcnt(6)
; #define LAS __attribute__((address_space(3)))
; __device__ __forceinline__ void dn_prep_item(const Args& a, LAS unsigned char* lds, int item, int tid, int wave, int lane, int& cwh, int next_item) {
;     ...
;         { const LAS float* lrow = Lm + (lane & 15);
; #pragma unroll
;         for (int i = 1; i < 64; ++i) { float sa[4] = { x[i], 0.f, 0.f, 0.f };
;             int lr[4];
; #pragma unroll
;             for (int g = 0; g < (i + 15) / 16; ++g) lr[g] = __float_as_int(lrow[i * 68 + 16 * g]);
; #pragma unroll
;             for (int j = 0; j < i; ++j) { fmac_rowbcast_sel(sa[j & 3], lr[j >> 4], x[j], j); }
;             x[i] = (sa[0] + sa[1]) + (sa[2] + sa[3]); } }
	s_nop 3
	v_mov_b32_e32 v235, v16
	s_nop 1
	v_mfma_f32_4x4x1_16b_f32 v[16:19], v120, v235, v[16:19]
	s_nop 1
	s_nop 3
	v_mov_b32_e32 v235, v17
	s_nop 1
	v_mfma_f32_4x4x1_16b_f32 v[16:19], v121, v235, v[16:19]
	s_nop 1
	s_nop 3
	v_mov_b32_e32 v235, v18
	s_nop 1
	v_mfma_f32_4x4x1_16b_f32 v[16:19], v122, v235, v[16:19]
	s_nop 1
	ds_read_b128 v[120:123], v234 offset:6528
	ds_read_b128 v[124:127], v234 offset:6544
	ds_read_b128 v[128:131], v234 offset:6560
	ds_read_b128 v[132:135], v234 offset:6576
	s_waitcnt lgkmcnt(6)
	s_nop 4
	v_mfma_f32_4x4x1_16b_f32 v[20:23], v88, v0, v[20:23]
	s_nop 1
	v_mfma_f32_4x4x1_16b_f32 v[20:23], v89, v1, v[20:23]
	s_nop 1
	v_mfma_f32_4x4x1_16b_f32 v[20:23], v90, v2, v[20:23]
	s_nop 1
	v_mfma_f32_4x4x1_16b_f32 v[20:23], v91, v3, v[20:23]
	s_nop 1
	v_mfma_f32_4x4x1_16b_f32 v[20:23], v92, v4, v[20:23]
	s_nop 1
	v_mfma_f32_4x4x1_16b_f32 v[20:23], v93, v5, v[20:23]
	s_nop 1
	v_mfma_f32_4x4x1_16b_f32 v[20:23], v94, v6, v[20:23]
	s_nop 1
	v_mfma_f32_4x4x1_16b_f32 v[20:23], v95, v7, v[20:23]
	s_nop 1
	v_mfma_f32_4x4x1_16b_f32 v[20:23], v96, v8, v[20:23]
	s_nop 1
	v_mfma_f32_4x4x1_16b_f32 v[20:23], v97, v9, v[20:23]
	s_nop 1
	v_mfma_f32_4x4x1_16b_f32 v[20:23], v98, v10, v[20:23]
	s_nop 1
	v_mfma_f32_4x4x1_16b_f32 v[20:23], v99, v11, v[20:23]
	s_nop 1
	v_mfma_f32_4x4x1_16b_f32 v[20:23], v100, v12, v[20:23]
	s_nop 1
	v_mfma_f32_4x4x1_16b_f32 v[20:23], v101, v13, v[20:23]
	s_nop 1
	v_mfma_f32_4x4x1_16b_f32 v[20:23], v102, v14, v[20:23]
	s_nop 1
	v_mfma_f32_4x4x1_16b_f32 v[20:23], v103, v15, v[20:23]
	s_nop 1
	ds_read_b128 v[88:91], v234 offset:6592
	ds_read_b128 v[92:95], v234 offset:6608
	ds_read_b128 v[96:99], v234 offset:6624
	s_waitcnt lgkmcnt(7)
	v_mfma_f32_4x4x1_16b_f32 v[20:23], v104, v16, v[20:23]
	s_nop 1
	v_mfma_f32_4x4x1_16b_f32 v[20:23], v105, v17, v[20:23]
	s_nop 1
	v_mfma_f32_4x4x1_16b_f32 v[20:23], v106, v18, v[20:23]
	s_nop 1
	v_mfma_f32_4x4x1_16b_f32 v[20:23], v107, v19, v[20:23]
	s_nop 1
	s_nop 3
	v_mov_b32_e32 v235, v20
	s_nop 1
	v_mfma_f32_4x4x1_16b_f32 v[20:23], v108, v235, v[20:23]
	s_nop 1
	s_nop 3
	v_mov_b32_e32 v235, v21
	s_nop 1
	v_mfma_f32_4x4x1_16b_f32 v[20:23], v109, v235, v[20:23]
	s_nop 1
	s_nop 3
	v_mov_b32_e32 v235, v22
	s_nop 1
	v_mfma_f32_4x4x1_16b_f32 v[20:23], v110, v235, v[20:23]
	s_nop 1
	ds_read_b128 v[104:107], v234 offset:7616
	ds_read_b128 v[108:111], v234 offset:7632
	ds_read_b128 v[112:115], v234 offset:7648
	ds_read_b128 v[116:119], v234 offset:7664
	s_waitcnt lgkmcnt(7)
	s_nop 4
	v_mfma_f32_4x4x1_16b_f32 v[24:27], v120, v0, v[24:27]
	s_nop 1
	v_mfma_f32_4x4x1_16b_f32 v[24:27], v121, v1, v[24:27]
	s_nop 1
	v_mfma_f32_4x4x1_16b_f32 v[24:27], v122, v2, v[24:27]
	s_nop 1
	v_mfma_f32_4x4x1_16b_f32 v[24:27], v123, v3, v[24:27]
	s_nop 1
	v_mfma_f32_4x4x1_16b_f32 v[24:27], v124, v4, v[24:27]
	s_nop 1
	v_mfma_f32_4x4x1_16b_f32 v[24:27], v125, v5, v[24:27]
	s_nop 1
	v_mfma_f32_4x4x1_16b_f32 v[24:27], v126, v6, v[24:27]
	s_nop 1
	v_mfma_f32_4x4x1_16b_f32 v[24:27], v127, v7, v[24:27]
	s_nop 1
	v_mfma_f32_4x4x1_16b_f32 v[24:27], v128, v8, v[24:27]
	s_nop 1
	v_mfma_f32_4x4x1_16b_f32 v[24:27], v129, v9, v[24:27]
	s_nop 1
	v_mfma_f32_4x4x1_16b_f32 v[24:27], v130, v10, v[24:27]
	s_nop 1
	v_mfma_f32_4x4x1_16b_f32 v[24:27], v131, v11, v[24:27]
	s_nop 1
	v_mfma_f32_4x4x1_16b_f32 v[24:27], v132, v12, v[24:27]
	s_nop 1
	v_mfma_f32_4x4x1_16b_f32 v[24:27], v133, v13, v[24:27]
	s_nop 1
	v_mfma_f32_4x4x1_16b_f32 v[24:27], v134, v14, v[24:27]
	s_nop 1
	v_mfma_f32_4x4x1_16b_f32 v[24:27], v135, v15, v[24:27]
	s_nop 1
	ds_read_b128 v[120:123], v234 offset:7680
	ds_read_b128 v[124:127], v234 offset:7696
	ds_read_b128 v[128:131], v234 offset:7712
	ds_read_b128 v[132:135], v234 offset:7728
	s_waitcnt lgkmcnt(8)
	v_mfma_f32_4x4x1_16b_f32 v[24:27], v88, v16, v[24:27]
	s_nop 1
	v_mfma_f32_4x4x1_16b_f32 v[24:27], v89, v17, v[24:27]
	s_nop 1
	v_mfma_f32_4x4x1_16b_f32 v[24:27], v90, v18, v[24:27]
	s_nop 1
	v_mfma_f32_4x4x1_16b_f32 v[24:27], v91, v19, v[24:27]
	s_nop 1
	v_mfma_f32_4x4x1_16b_f32 v[24:27], v92, v20, v[24:27]
	s_nop 1
	v_mfma_f32_4x4x1_16b_f32 v[24:27], v93, v21, v[24:27]
	s_nop 1
	v_mfma_f32_4x4x1_16b_f32 v[24:27], v94, v22, v[24:27]
	s_nop 1
	v_mfma_f32_4x4x1_16b_f32 v[24:27], v95, v23, v[24:27]
	s_nop 1
	s_nop 3
	v_mov_b32_e32 v235, v24
	s_nop 1
	v_mfma_f32_4x4x1_16b_f32 v[24:27], v96, v235, v[24:27]
	s_nop 1
	s_nop 3
	v_mov_b32_e32 v235, v25
	s_nop 1
	v_mfma_f32_4x4x1_16b_f32 v[24:27], v97, v235, v[24:27]
	s_nop 1
	s_nop 3
	v_mov_b32_e32 v235, v26
	s_nop 1
	v_mfma_f32_4x4x1_16b_f32 v[24:27], v98, v235, v[24:27]
	s_nop 1
	ds_read_b128 v[88:91], v234 offset:8704
	ds_read_b128 v[92:95], v234 offset:8720
	ds_read_b128 v[96:99], v234 offset:8736
	ds_read_b128 v[100:103], v234 offset:8752
	s_waitcnt lgkmcnt(8)
	s_nop 4
	v_mfma_f32_4x4x1_16b_f32 v[28:31], v104, v0, v[28:31]
	s_nop 1
	v_mfma_f32_4x4x1_16b_f32 v[28:31], v105, v1, v[28:31]
	s_nop 1
	v_mfma_f32_4x4x1_16b_f32 v[28:31], v106, v2, v[28:31]
	s_nop 1
	v_mfma_f32_4x4x1_16b_f32 v[28:31], v107, v3, v[28:31]
	s_nop 1
	v_mfma_f32_4x4x1_16b_f32 v[28:31], v108, v4, v[28:31]
	s_nop 1
	v_mfma_f32_4x4x1_16b_f32 v[28:31], v109, v5, v[28:31]
	s_nop 1
	v_mfma_f32_4x4x1_16b_f32 v[28:31], v110, v6, v[28:31]
	s_nop 1
	v_mfma_f32_4x4x1_16b_f32 v[28:31], v111, v7, v[28:31]
	s_nop 1
	v_mfma_f32_4x4x1_16b_f32 v[28:31], v112, v8, v[28:31]
	s_nop 1
	v_mfma_f32_4x4x1_16b_f32 v[28:31], v113, v9, v[28:31]
	s_nop 1
	v_mfma_f32_4x4x1_16b_f32 v[28:31], v114, v10, v[28:31]
	s_nop 1
	v_mfma_f32_4x4x1_16b_f32 v[28:31], v115, v11, v[28:31]
	s_nop 1
	v_mfma_f32_4x4x1_16b_f32 v[28:31], v116, v12, v[28:31]
	s_nop 1
	v_mfma_f32_4x4x1_16b_f32 v[28:31], v117, v13, v[28:31]
	s_nop 1
	v_mfma_f32_4x4x1_16b_f32 v[28:31], v118, v14, v[28:31]
	s_nop 1
	v_mfma_f32_4x4x1_16b_f32 v[28:31], v119, v15, v[28:31]
	s_nop 1
	ds_read_b128 v[104:107], v234 offset:8768
	ds_read_b128 v[108:111], v234 offset:8784
	ds_read_b128 v[112:115], v234 offset:8800
	ds_read_b128 v[116:119], v234 offset:8816
	s_waitcnt lgkmcnt(8)
; #define LAS __attribute__((address_space(3)))
; __device__ __forceinline__ void dn_prep_item(const Args& a, LAS unsigned char* lds, int item, int tid, int wave, int lane, int& cwh, int next_item) {
;     ...
;         { const LAS float* lrow = Lm + (lane & 15);
; #pragma unroll
;         for (int i = 1; i < 64; ++i) { float sa[4] = { x[i], 0.f, 0.f, 0.f };
;             int lr[4];
; #pragma unroll
;             for (int g = 0; g < (i + 15) / 16; ++g) lr[g] = __float_as_int(lrow[i * 68 + 16 * g]);
; #pragma unroll
;             for (int j = 0; j < i; ++j) { fmac_rowbcast_sel(sa[j & 3], lr[j >> 4], x[j], j); }
;             x[i] = (sa[0] + sa[1]) + (sa[2] + sa[3]); } }
	v_mfma_f32_4x4x1_16b_f32 v[28:31], v120, v16, v[28:31]
	s_nop 1
	v_mfma_f32_4x4x1_16b_f32 v[28:31], v121, v17, v[28:31]
	s_nop 1
	v_mfma_f32_4x4x1_16b_f32 v[28:31], v122, v18, v[28:31]
	s_nop 1
	v_mfma_f32_4x4x1_16b_f32 v[28:31], v123, v19, v[28:31]
	s_nop 1
	v_mfma_f32_4x4x1_16b_f32 v[28:31], v124, v20, v[28:31]
	s_nop 1
	v_mfma_f32_4x4x1_16b_f32 v[28:31], v125, v21, v[28:31]
	s_nop 1
	v_mfma_f32_4x4x1_16b_f32 v[28:31], v126, v22, v[28:31]
	s_nop 1
	v_mfma_f32_4x4x1_16b_f32 v[28:31], v127, v23, v[28:31]
	s_nop 1
	v_mfma_f32_4x4x1_16b_f32 v[28:31], v128, v24, v[28:31]
	s_nop 1
	v_mfma_f32_4x4x1_16b_f32 v[28:31], v129, v25, v[28:31]
	s_nop 1
	v_mfma_f32_4x4x1_16b_f32 v[28:31], v130, v26, v[28:31]
	s_nop 1
	v_mfma_f32_4x4x1_16b_f32 v[28:31], v131, v27, v[28:31]
	s_nop 1
	s_nop 3
	v_mov_b32_e32 v235, v28
	s_nop 1
	v_mfma_f32_4x4x1_16b_f32 v[28:31], v132, v235, v[28:31]
	s_nop 1
	s_nop 3
	v_mov_b32_e32 v235, v29
	s_nop 1
	v_mfma_f32_4x4x1_16b_f32 v[28:31], v133, v235, v[28:31]
	s_nop 1
	s_nop 3
	v_mov_b32_e32 v235, v30
	s_nop 1
	v_mfma_f32_4x4x1_16b_f32 v[28:31], v134, v235, v[28:31]
	s_nop 1
	ds_read_b128 v[120:123], v234 offset:8832
	s_waitcnt lgkmcnt(5)
	s_nop 4
	v_mfma_f32_4x4x1_16b_f32 v[32:35], v88, v0, v[32:35]
	s_nop 1
	v_mfma_f32_4x4x1_16b_f32 v[32:35], v89, v1, v[32:35]
	s_nop 1
	v_mfma_f32_4x4x1_16b_f32 v[32:35], v90, v2, v[32:35]
	s_nop 1
	v_mfma_f32_4x4x1_16b_f32 v[32:35], v91, v3, v[32:35]
	s_nop 1
	v_mfma_f32_4x4x1_16b_f32 v[32:35], v92, v4, v[32:35]
	s_nop 1
	v_mfma_f32_4x4x1_16b_f32 v[32:35], v93, v5, v[32:35]
	s_nop 1
	v_mfma_f32_4x4x1_16b_f32 v[32:35], v94, v6, v[32:35]
	s_nop 1
	v_mfma_f32_4x4x1_16b_f32 v[32:35], v95, v7, v[32:35]
	s_nop 1
	v_mfma_f32_4x4x1_16b_f32 v[32:35], v96, v8, v[32:35]
	s_nop 1
	v_mfma_f32_4x4x1_16b_f32 v[32:35], v97, v9, v[32:35]
	s_nop 1
	v_mfma_f32_4x4x1_16b_f32 v[32:35], v98, v10, v[32:35]
	s_nop 1
	v_mfma_f32_4x4x1_16b_f32 v[32:35], v99, v11, v[32:35]
	s_nop 1
	v_mfma_f32_4x4x1_16b_f32 v[32:35], v100, v12, v[32:35]
	s_nop 1
	v_mfma_f32_4x4x1_16b_f32 v[32:35], v101, v13, v[32:35]
	s_nop 1
	v_mfma_f32_4x4x1_16b_f32 v[32:35], v102, v14, v[32:35]
	s_nop 1
	v_mfma_f32_4x4x1_16b_f32 v[32:35], v103, v15, v[32:35]
	s_nop 1
	ds_read_b128 v[88:91], v234 offset:9792
	ds_read_b128 v[92:95], v234 offset:9808
	ds_read_b128 v[96:99], v234 offset:9824
	ds_read_b128 v[100:103], v234 offset:9840
	s_waitcnt lgkmcnt(5)
	v_mfma_f32_4x4x1_16b_f32 v[32:35], v104, v16, v[32:35]
	s_nop 1
	v_mfma_f32_4x4x1_16b_f32 v[32:35], v105, v17, v[32:35]
	s_nop 1
	v_mfma_f32_4x4x1_16b_f32 v[32:35], v106, v18, v[32:35]
	s_nop 1
	v_mfma_f32_4x4x1_16b_f32 v[32:35], v107, v19, v[32:35]
	s_nop 1
	v_mfma_f32_4x4x1_16b_f32 v[32:35], v108, v20, v[32:35]
	s_nop 1
	v_mfma_f32_4x4x1_16b_f32 v[32:35], v109, v21, v[32:35]
	s_nop 1
	v_mfma_f32_4x4x1_16b_f32 v[32:35], v110, v22, v[32:35]
	s_nop 1
	v_mfma_f32_4x4x1_16b_f32 v[32:35], v111, v23, v[32:35]
	s_nop 1
	v_mfma_f32_4x4x1_16b_f32 v[32:35], v112, v24, v[32:35]
	s_nop 1
	v_mfma_f32_4x4x1_16b_f32 v[32:35], v113, v25, v[32:35]
	s_nop 1
	v_mfma_f32_4x4x1_16b_f32 v[32:35], v114, v26, v[32:35]
	s_nop 1
	v_mfma_f32_4x4x1_16b_f32 v[32:35], v115, v27, v[32:35]
	s_nop 1
	v_mfma_f32_4x4x1_16b_f32 v[32:35], v116, v28, v[32:35]
	s_nop 1
	v_mfma_f32_4x4x1_16b_f32 v[32:35], v117, v29, v[32:35]
	s_nop 1
	v_mfma_f32_4x4x1_16b_f32 v[32:35], v118, v30, v[32:35]
	s_nop 1
	v_mfma_f32_4x4x1_16b_f32 v[32:35], v119, v31, v[32:35]
	s_nop 1
	ds_read_b128 v[104:107], v234 offset:9856
	ds_read_b128 v[108:111], v234 offset:9872
	ds_read_b128 v[112:115], v234 offset:9888
	ds_read_b128 v[116:119], v234 offset:9904
	s_waitcnt lgkmcnt(8)
	s_nop 3
	v_mov_b32_e32 v235, v32
	s_nop 1
	v_mfma_f32_4x4x1_16b_f32 v[32:35], v120, v235, v[32:35]
	s_nop 1
	s_nop 3
	v_mov_b32_e32 v235, v33
	s_nop 1
	v_mfma_f32_4x4x1_16b_f32 v[32:35], v121, v235, v[32:35]
	s_nop 1
	s_nop 3
	v_mov_b32_e32 v235, v34
	s_nop 1
	v_mfma_f32_4x4x1_16b_f32 v[32:35], v122, v235, v[32:35]
	s_nop 1
	ds_read_b128 v[120:123], v234 offset:9920
	ds_read_b128 v[124:127], v234 offset:9936
	s_waitcnt lgkmcnt(6)
	s_nop 4
	v_mfma_f32_4x4x1_16b_f32 v[36:39], v88, v0, v[36:39]
	s_nop 1
	v_mfma_f32_4x4x1_16b_f32 v[36:39], v89, v1, v[36:39]
	s_nop 1
	v_mfma_f32_4x4x1_16b_f32 v[36:39], v90, v2, v[36:39]
	s_nop 1
	v_mfma_f32_4x4x1_16b_f32 v[36:39], v91, v3, v[36:39]
	s_nop 1
	v_mfma_f32_4x4x1_16b_f32 v[36:39], v92, v4, v[36:39]
	s_nop 1
	v_mfma_f32_4x4x1_16b_f32 v[36:39], v93, v5, v[36:39]
	s_nop 1
	v_mfma_f32_4x4x1_16b_f32 v[36:39], v94, v6, v[36:39]
	s_nop 1
	v_mfma_f32_4x4x1_16b_f32 v[36:39], v95, v7, v[36:39]
	s_nop 1
	v_mfma_f32_4x4x1_16b_f32 v[36:39], v96, v8, v[36:39]
	s_nop 1
	v_mfma_f32_4x4x1_16b_f32 v[36:39], v97, v9, v[36:39]
	s_nop 1
	v_mfma_f32_4x4x1_16b_f32 v[36:39], v98, v10, v[36:39]
	s_nop 1
	v_mfma_f32_4x4x1_16b_f32 v[36:39], v99, v11, v[36:39]
	s_nop 1
	v_mfma_f32_4x4x1_16b_f32 v[36:39], v100, v12, v[36:39]
	s_nop 1
	v_mfma_f32_4x4x1_16b_f32 v[36:39], v101, v13, v[36:39]
	s_nop 1
	v_mfma_f32_4x4x1_16b_f32 v[36:39], v102, v14, v[36:39]
	s_nop 1
	v_mfma_f32_4x4x1_16b_f32 v[36:39], v103, v15, v[36:39]
	s_nop 1
	ds_read_b128 v[88:91], v234 offset:10880
	ds_read_b128 v[92:95], v234 offset:10896
	ds_read_b128 v[96:99], v234 offset:10912
	ds_read_b128 v[100:103], v234 offset:10928
	s_waitcnt lgkmcnt(6)
; #define LAS __attribute__((address_space(3)))
; __device__ __forceinline__ void dn_prep_item(const Args& a, LAS unsigned char* lds, int item, int tid, int wave, int lane, int& cwh, int next_item) {
;     ...
;         { const LAS float* lrow = Lm + (lane & 15);
; #pragma unroll
;         for (int i = 1; i < 64; ++i) { float sa[4] = { x[i], 0.f, 0.f, 0.f };
;             int lr[4];
; #pragma unroll
;             for (int g = 0; g < (i + 15) / 16; ++g) lr[g] = __float_as_int(lrow[i * 68 + 16 * g]);
; #pragma unroll
;             for (int j = 0; j < i; ++j) { fmac_rowbcast_sel(sa[j & 3], lr[j >> 4], x[j], j); }
;             x[i] = (sa[0] + sa[1]) + (sa[2] + sa[3]); } }
	v_mfma_f32_4x4x1_16b_f32 v[36:39], v104, v16, v[36:39]
	s_nop 1
	v_mfma_f32_4x4x1_16b_f32 v[36:39], v105, v17, v[36:39]
	s_nop 1
	v_mfma_f32_4x4x1_16b_f32 v[36:39], v106, v18, v[36:39]
	s_nop 1
	v_mfma_f32_4x4x1_16b_f32 v[36:39], v107, v19, v[36:39]
	s_nop 1
	v_mfma_f32_4x4x1_16b_f32 v[36:39], v108, v20, v[36:39]
	s_nop 1
	v_mfma_f32_4x4x1_16b_f32 v[36:39], v109, v21, v[36:39]
	s_nop 1
	v_mfma_f32_4x4x1_16b_f32 v[36:39], v110, v22, v[36:39]
	s_nop 1
	v_mfma_f32_4x4x1_16b_f32 v[36:39], v111, v23, v[36:39]
	s_nop 1
	v_mfma_f32_4x4x1_16b_f32 v[36:39], v112, v24, v[36:39]
	s_nop 1
	v_mfma_f32_4x4x1_16b_f32 v[36:39], v113, v25, v[36:39]
	s_nop 1
	v_mfma_f32_4x4x1_16b_f32 v[36:39], v114, v26, v[36:39]
	s_nop 1
	v_mfma_f32_4x4x1_16b_f32 v[36:39], v115, v27, v[36:39]
	s_nop 1
	v_mfma_f32_4x4x1_16b_f32 v[36:39], v116, v28, v[36:39]
	s_nop 1
	v_mfma_f32_4x4x1_16b_f32 v[36:39], v117, v29, v[36:39]
	s_nop 1
	v_mfma_f32_4x4x1_16b_f32 v[36:39], v118, v30, v[36:39]
	s_nop 1
	v_mfma_f32_4x4x1_16b_f32 v[36:39], v119, v31, v[36:39]
	s_nop 1
	ds_read_b128 v[104:107], v234 offset:10944
	ds_read_b128 v[108:111], v234 offset:10960
	ds_read_b128 v[112:115], v234 offset:10976
	ds_read_b128 v[116:119], v234 offset:10992
	s_waitcnt lgkmcnt(8)
	v_mfma_f32_4x4x1_16b_f32 v[36:39], v120, v32, v[36:39]
	s_nop 1
	v_mfma_f32_4x4x1_16b_f32 v[36:39], v121, v33, v[36:39]
	s_nop 1
	v_mfma_f32_4x4x1_16b_f32 v[36:39], v122, v34, v[36:39]
	s_nop 1
	v_mfma_f32_4x4x1_16b_f32 v[36:39], v123, v35, v[36:39]
	s_nop 1
	s_nop 3
	v_mov_b32_e32 v235, v36
	s_nop 1
	v_mfma_f32_4x4x1_16b_f32 v[36:39], v124, v235, v[36:39]
	s_nop 1
	s_nop 3
	v_mov_b32_e32 v235, v37
	s_nop 1
	v_mfma_f32_4x4x1_16b_f32 v[36:39], v125, v235, v[36:39]
	s_nop 1
	s_nop 3
	v_mov_b32_e32 v235, v38
	s_nop 1
	v_mfma_f32_4x4x1_16b_f32 v[36:39], v126, v235, v[36:39]
	s_nop 1
	ds_read_b128 v[120:123], v234 offset:11008
	ds_read_b128 v[124:127], v234 offset:11024
	ds_read_b128 v[128:131], v234 offset:11040
	s_waitcnt lgkmcnt(7)
	s_nop 4
	v_mfma_f32_4x4x1_16b_f32 v[40:43], v88, v0, v[40:43]
	s_nop 1
	v_mfma_f32_4x4x1_16b_f32 v[40:43], v89, v1, v[40:43]
	s_nop 1
	v_mfma_f32_4x4x1_16b_f32 v[40:43], v90, v2, v[40:43]
	s_nop 1
	v_mfma_f32_4x4x1_16b_f32 v[40:43], v91, v3, v[40:43]
	s_nop 1
	v_mfma_f32_4x4x1_16b_f32 v[40:43], v92, v4, v[40:43]
	s_nop 1
	v_mfma_f32_4x4x1_16b_f32 v[40:43], v93, v5, v[40:43]
	s_nop 1
	v_mfma_f32_4x4x1_16b_f32 v[40:43], v94, v6, v[40:43]
	s_nop 1
	v_mfma_f32_4x4x1_16b_f32 v[40:43], v95, v7, v[40:43]
	s_nop 1
	v_mfma_f32_4x4x1_16b_f32 v[40:43], v96, v8, v[40:43]
	s_nop 1
	v_mfma_f32_4x4x1_16b_f32 v[40:43], v97, v9, v[40:43]
	s_nop 1
	v_mfma_f32_4x4x1_16b_f32 v[40:43], v98, v10, v[40:43]
	s_nop 1
	v_mfma_f32_4x4x1_16b_f32 v[40:43], v99, v11, v[40:43]
	s_nop 1
	v_mfma_f32_4x4x1_16b_f32 v[40:43], v100, v12, v[40:43]
	s_nop 1
	v_mfma_f32_4x4x1_16b_f32 v[40:43], v101, v13, v[40:43]
	s_nop 1
	v_mfma_f32_4x4x1_16b_f32 v[40:43], v102, v14, v[40:43]
	s_nop 1
	v_mfma_f32_4x4x1_16b_f32 v[40:43], v103, v15, v[40:43]
	s_nop 1
	ds_read_b128 v[88:91], v234 offset:11968
	ds_read_b128 v[92:95], v234 offset:11984
	ds_read_b128 v[96:99], v234 offset:12000
	ds_read_b128 v[100:103], v234 offset:12016
	s_waitcnt lgkmcnt(7)
	v_mfma_f32_4x4x1_16b_f32 v[40:43], v104, v16, v[40:43]
	s_nop 1
	v_mfma_f32_4x4x1_16b_f32 v[40:43], v105, v17, v[40:43]
	s_nop 1
	v_mfma_f32_4x4x1_16b_f32 v[40:43], v106, v18, v[40:43]
	s_nop 1
	v_mfma_f32_4x4x1_16b_f32 v[40:43], v107, v19, v[40:43]
	s_nop 1
	v_mfma_f32_4x4x1_16b_f32 v[40:43], v108, v20, v[40:43]
	s_nop 1
	v_mfma_f32_4x4x1_16b_f32 v[40:43], v109, v21, v[40:43]
	s_nop 1
	v_mfma_f32_4x4x1_16b_f32 v[40:43], v110, v22, v[40:43]
	s_nop 1
	v_mfma_f32_4x4x1_16b_f32 v[40:43], v111, v23, v[40:43]
	s_nop 1
	v_mfma_f32_4x4x1_16b_f32 v[40:43], v112, v24, v[40:43]
	s_nop 1
	v_mfma_f32_4x4x1_16b_f32 v[40:43], v113, v25, v[40:43]
	s_nop 1
	v_mfma_f32_4x4x1_16b_f32 v[40:43], v114, v26, v[40:43]
	s_nop 1
	v_mfma_f32_4x4x1_16b_f32 v[40:43], v115, v27, v[40:43]
	s_nop 1
	v_mfma_f32_4x4x1_16b_f32 v[40:43], v116, v28, v[40:43]
	s_nop 1
	v_mfma_f32_4x4x1_16b_f32 v[40:43], v117, v29, v[40:43]
	s_nop 1
	v_mfma_f32_4x4x1_16b_f32 v[40:43], v118, v30, v[40:43]
	s_nop 1
	v_mfma_f32_4x4x1_16b_f32 v[40:43], v119, v31, v[40:43]
	s_nop 1
	ds_read_b128 v[104:107], v234 offset:12032
	ds_read_b128 v[108:111], v234 offset:12048
	ds_read_b128 v[112:115], v234 offset:12064
	ds_read_b128 v[116:119], v234 offset:12080
	s_waitcnt lgkmcnt(8)
	v_mfma_f32_4x4x1_16b_f32 v[40:43], v120, v32, v[40:43]
	s_nop 1
	v_mfma_f32_4x4x1_16b_f32 v[40:43], v121, v33, v[40:43]
	s_nop 1
	v_mfma_f32_4x4x1_16b_f32 v[40:43], v122, v34, v[40:43]
	s_nop 1
	v_mfma_f32_4x4x1_16b_f32 v[40:43], v123, v35, v[40:43]
	s_nop 1
	v_mfma_f32_4x4x1_16b_f32 v[40:43], v124, v36, v[40:43]
	s_nop 1
	v_mfma_f32_4x4x1_16b_f32 v[40:43], v125, v37, v[40:43]
	s_nop 1
	v_mfma_f32_4x4x1_16b_f32 v[40:43], v126, v38, v[40:43]
	s_nop 1
	v_mfma_f32_4x4x1_16b_f32 v[40:43], v127, v39, v[40:43]
	s_nop 1
	s_nop 3
	v_mov_b32_e32 v235, v40
	s_nop 1
	v_mfma_f32_4x4x1_16b_f32 v[40:43], v128, v235, v[40:43]
	s_nop 1
	s_nop 3
	v_mov_b32_e32 v235, v41
	s_nop 1
	v_mfma_f32_4x4x1_16b_f32 v[40:43], v129, v235, v[40:43]
	s_nop 1
	s_nop 3
	v_mov_b32_e32 v235, v42
	s_nop 1
	v_mfma_f32_4x4x1_16b_f32 v[40:43], v130, v235, v[40:43]
	s_nop 1
	ds_read_b128 v[120:123], v234 offset:12096
	ds_read_b128 v[124:127], v234 offset:12112
	ds_read_b128 v[128:131], v234 offset:12128
	ds_read_b128 v[132:135], v234 offset:12144
	s_waitcnt lgkmcnt(8)
; #define LAS __attribute__((address_space(3)))
; __device__ __forceinline__ void dn_prep_item(const Args& a, LAS unsigned char* lds, int item, int tid, int wave, int lane, int& cwh, int next_item) {
;     ...
;         { const LAS float* lrow = Lm + (lane & 15);
; #pragma unroll
;         for (int i = 1; i < 64; ++i) { float sa[4] = { x[i], 0.f, 0.f, 0.f };
;             int lr[4];
; #pragma unroll
;             for (int g = 0; g < (i + 15) / 16; ++g) lr[g] = __float_as_int(lrow[i * 68 + 16 * g]);
; #pragma unroll
;             for (int j = 0; j < i; ++j) { fmac_rowbcast_sel(sa[j & 3], lr[j >> 4], x[j], j); }
;             x[i] = (sa[0] + sa[1]) + (sa[2] + sa[3]); } }
	s_nop 4
	v_mfma_f32_4x4x1_16b_f32 v[44:47], v88, v0, v[44:47]
	s_nop 1
	v_mfma_f32_4x4x1_16b_f32 v[44:47], v89, v1, v[44:47]
	s_nop 1
	v_mfma_f32_4x4x1_16b_f32 v[44:47], v90, v2, v[44:47]
	s_nop 1
	v_mfma_f32_4x4x1_16b_f32 v[44:47], v91, v3, v[44:47]
	s_nop 1
	v_mfma_f32_4x4x1_16b_f32 v[44:47], v92, v4, v[44:47]
	s_nop 1
	v_mfma_f32_4x4x1_16b_f32 v[44:47], v93, v5, v[44:47]
	s_nop 1
	v_mfma_f32_4x4x1_16b_f32 v[44:47], v94, v6, v[44:47]
	s_nop 1
	v_mfma_f32_4x4x1_16b_f32 v[44:47], v95, v7, v[44:47]
	s_nop 1
	v_mfma_f32_4x4x1_16b_f32 v[44:47], v96, v8, v[44:47]
	s_nop 1
	v_mfma_f32_4x4x1_16b_f32 v[44:47], v97, v9, v[44:47]
	s_nop 1
	v_mfma_f32_4x4x1_16b_f32 v[44:47], v98, v10, v[44:47]
	s_nop 1
	v_mfma_f32_4x4x1_16b_f32 v[44:47], v99, v11, v[44:47]
	s_nop 1
	v_mfma_f32_4x4x1_16b_f32 v[44:47], v100, v12, v[44:47]
	s_nop 1
	v_mfma_f32_4x4x1_16b_f32 v[44:47], v101, v13, v[44:47]
	s_nop 1
	v_mfma_f32_4x4x1_16b_f32 v[44:47], v102, v14, v[44:47]
	s_nop 1
	v_mfma_f32_4x4x1_16b_f32 v[44:47], v103, v15, v[44:47]
	s_nop 1
	ds_read_b128 v[88:91], v234 offset:13056
	ds_read_b128 v[92:95], v234 offset:13072
	ds_read_b128 v[96:99], v234 offset:13088
	ds_read_b128 v[100:103], v234 offset:13104
	s_waitcnt lgkmcnt(8)
	v_mfma_f32_4x4x1_16b_f32 v[44:47], v104, v16, v[44:47]
	s_nop 1
	v_mfma_f32_4x4x1_16b_f32 v[44:47], v105, v17, v[44:47]
	s_nop 1
	v_mfma_f32_4x4x1_16b_f32 v[44:47], v106, v18, v[44:47]
	s_nop 1
	v_mfma_f32_4x4x1_16b_f32 v[44:47], v107, v19, v[44:47]
	s_nop 1
	v_mfma_f32_4x4x1_16b_f32 v[44:47], v108, v20, v[44:47]
	s_nop 1
	v_mfma_f32_4x4x1_16b_f32 v[44:47], v109, v21, v[44:47]
	s_nop 1
	v_mfma_f32_4x4x1_16b_f32 v[44:47], v110, v22, v[44:47]
	s_nop 1
	v_mfma_f32_4x4x1_16b_f32 v[44:47], v111, v23, v[44:47]
	s_nop 1
	v_mfma_f32_4x4x1_16b_f32 v[44:47], v112, v24, v[44:47]
	s_nop 1
	v_mfma_f32_4x4x1_16b_f32 v[44:47], v113, v25, v[44:47]
	s_nop 1
	v_mfma_f32_4x4x1_16b_f32 v[44:47], v114, v26, v[44:47]
	s_nop 1
	v_mfma_f32_4x4x1_16b_f32 v[44:47], v115, v27, v[44:47]
	s_nop 1
	v_mfma_f32_4x4x1_16b_f32 v[44:47], v116, v28, v[44:47]
	s_nop 1
	v_mfma_f32_4x4x1_16b_f32 v[44:47], v117, v29, v[44:47]
	s_nop 1
	v_mfma_f32_4x4x1_16b_f32 v[44:47], v118, v30, v[44:47]
	s_nop 1
	v_mfma_f32_4x4x1_16b_f32 v[44:47], v119, v31, v[44:47]
	s_nop 1
	ds_read_b128 v[104:107], v234 offset:13120
	ds_read_b128 v[108:111], v234 offset:13136
	ds_read_b128 v[112:115], v234 offset:13152
	ds_read_b128 v[116:119], v234 offset:13168
	s_waitcnt lgkmcnt(8)
	v_mfma_f32_4x4x1_16b_f32 v[44:47], v120, v32, v[44:47]
	s_nop 1
	v_mfma_f32_4x4x1_16b_f32 v[44:47], v121, v33, v[44:47]
	s_nop 1
	v_mfma_f32_4x4x1_16b_f32 v[44:47], v122, v34, v[44:47]
	s_nop 1
	v_mfma_f32_4x4x1_16b_f32 v[44:47], v123, v35, v[44:47]
	s_nop 1
	v_mfma_f32_4x4x1_16b_f32 v[44:47], v124, v36, v[44:47]
	s_nop 1
	v_mfma_f32_4x4x1_16b_f32 v[44:47], v125, v37, v[44:47]
	s_nop 1
	v_mfma_f32_4x4x1_16b_f32 v[44:47], v126, v38, v[44:47]
	s_nop 1
	v_mfma_f32_4x4x1_16b_f32 v[44:47], v127, v39, v[44:47]
	s_nop 1
	v_mfma_f32_4x4x1_16b_f32 v[44:47], v128, v40, v[44:47]
	s_nop 1
	v_mfma_f32_4x4x1_16b_f32 v[44:47], v129, v41, v[44:47]
	s_nop 1
	v_mfma_f32_4x4x1_16b_f32 v[44:47], v130, v42, v[44:47]
	s_nop 1
	v_mfma_f32_4x4x1_16b_f32 v[44:47], v131, v43, v[44:47]
	s_nop 1
	s_nop 3
	v_mov_b32_e32 v235, v44
	s_nop 1
	v_mfma_f32_4x4x1_16b_f32 v[44:47], v132, v235, v[44:47]
	s_nop 1
	s_nop 3
	v_mov_b32_e32 v235, v45
	s_nop 1
	v_mfma_f32_4x4x1_16b_f32 v[44:47], v133, v235, v[44:47]
	s_nop 1
	s_nop 3
	v_mov_b32_e32 v235, v46
	s_nop 1
	v_mfma_f32_4x4x1_16b_f32 v[44:47], v134, v235, v[44:47]
	s_nop 1
	ds_read_b128 v[120:123], v234 offset:13184
	ds_read_b128 v[124:127], v234 offset:13200
	ds_read_b128 v[128:131], v234 offset:13216
	ds_read_b128 v[132:135], v234 offset:13232
	s_waitcnt lgkmcnt(8)
	s_nop 4
	v_mfma_f32_4x4x1_16b_f32 v[72:75], v88, v0, v[72:75]
	s_nop 1
	v_mfma_f32_4x4x1_16b_f32 v[72:75], v89, v1, v[72:75]
	s_nop 1
	v_mfma_f32_4x4x1_16b_f32 v[72:75], v90, v2, v[72:75]
	s_nop 1
	v_mfma_f32_4x4x1_16b_f32 v[72:75], v91, v3, v[72:75]
	s_nop 1
	v_mfma_f32_4x4x1_16b_f32 v[72:75], v92, v4, v[72:75]
	s_nop 1
	v_mfma_f32_4x4x1_16b_f32 v[72:75], v93, v5, v[72:75]
	s_nop 1
	v_mfma_f32_4x4x1_16b_f32 v[72:75], v94, v6, v[72:75]
	s_nop 1
	v_mfma_f32_4x4x1_16b_f32 v[72:75], v95, v7, v[72:75]
	s_nop 1
	v_mfma_f32_4x4x1_16b_f32 v[72:75], v96, v8, v[72:75]
	s_nop 1
	v_mfma_f32_4x4x1_16b_f32 v[72:75], v97, v9, v[72:75]
	s_nop 1
	v_mfma_f32_4x4x1_16b_f32 v[72:75], v98, v10, v[72:75]
	s_nop 1
	v_mfma_f32_4x4x1_16b_f32 v[72:75], v99, v11, v[72:75]
	s_nop 1
	v_mfma_f32_4x4x1_16b_f32 v[72:75], v100, v12, v[72:75]
	s_nop 1
	v_mfma_f32_4x4x1_16b_f32 v[72:75], v101, v13, v[72:75]
	s_nop 1
	v_mfma_f32_4x4x1_16b_f32 v[72:75], v102, v14, v[72:75]
	s_nop 1
	v_mfma_f32_4x4x1_16b_f32 v[72:75], v103, v15, v[72:75]
	s_nop 1
	ds_read_b128 v[88:91], v234 offset:13248
	s_waitcnt lgkmcnt(5)
	v_mfma_f32_4x4x1_16b_f32 v[72:75], v104, v16, v[72:75]
	s_nop 1
	v_mfma_f32_4x4x1_16b_f32 v[72:75], v105, v17, v[72:75]
	s_nop 1
	v_mfma_f32_4x4x1_16b_f32 v[72:75], v106, v18, v[72:75]
	s_nop 1
	v_mfma_f32_4x4x1_16b_f32 v[72:75], v107, v19, v[72:75]
	s_nop 1
	v_mfma_f32_4x4x1_16b_f32 v[72:75], v108, v20, v[72:75]
	s_nop 1
	v_mfma_f32_4x4x1_16b_f32 v[72:75], v109, v21, v[72:75]
	s_nop 1
	v_mfma_f32_4x4x1_16b_f32 v[72:75], v110, v22, v[72:75]
	s_nop 1
	v_mfma_f32_4x4x1_16b_f32 v[72:75], v111, v23, v[72:75]
	s_nop 1
	v_mfma_f32_4x4x1_16b_f32 v[72:75], v112, v24, v[72:75]
	s_nop 1
	v_mfma_f32_4x4x1_16b_f32 v[72:75], v113, v25, v[72:75]
	s_nop 1
	v_mfma_f32_4x4x1_16b_f32 v[72:75], v114, v26, v[72:75]
	s_nop 1
	v_mfma_f32_4x4x1_16b_f32 v[72:75], v115, v27, v[72:75]
	s_nop 1
	v_mfma_f32_4x4x1_16b_f32 v[72:75], v116, v28, v[72:75]
	s_nop 1
	v_mfma_f32_4x4x1_16b_f32 v[72:75], v117, v29, v[72:75]
	s_nop 1
	v_mfma_f32_4x4x1_16b_f32 v[72:75], v118, v30, v[72:75]
	s_nop 1
	v_mfma_f32_4x4x1_16b_f32 v[72:75], v119, v31, v[72:75]
	s_nop 1
	ds_read_b128 v[104:107], v234 offset:14144
	ds_read_b128 v[108:111], v234 offset:14160
	ds_read_b128 v[112:115], v234 offset:14176
	ds_read_b128 v[116:119], v234 offset:14192
	s_waitcnt lgkmcnt(5)
; #define LAS __attribute__((address_space(3)))
; __device__ __forceinline__ void dn_prep_item(const Args& a, LAS unsigned char* lds, int item, int tid, int wave, int lane, int& cwh, int next_item) {
;     ...
;         { const LAS float* lrow = Lm + (lane & 15);
; #pragma unroll
;         for (int i = 1; i < 64; ++i) { float sa[4] = { x[i], 0.f, 0.f, 0.f };
;             int lr[4];
; #pragma unroll
;             for (int g = 0; g < (i + 15) / 16; ++g) lr[g] = __float_as_int(lrow[i * 68 + 16 * g]);
; #pragma unroll
;             for (int j = 0; j < i; ++j) { fmac_rowbcast_sel(sa[j & 3], lr[j >> 4], x[j], j); }
;             x[i] = (sa[0] + sa[1]) + (sa[2] + sa[3]); } }
	v_mfma_f32_4x4x1_16b_f32 v[72:75], v120, v32, v[72:75]
	s_nop 1
	v_mfma_f32_4x4x1_16b_f32 v[72:75], v121, v33, v[72:75]
	s_nop 1
	v_mfma_f32_4x4x1_16b_f32 v[72:75], v122, v34, v[72:75]
	s_nop 1
	v_mfma_f32_4x4x1_16b_f32 v[72:75], v123, v35, v[72:75]
	s_nop 1
	v_mfma_f32_4x4x1_16b_f32 v[72:75], v124, v36, v[72:75]
	s_nop 1
	v_mfma_f32_4x4x1_16b_f32 v[72:75], v125, v37, v[72:75]
	s_nop 1
	v_mfma_f32_4x4x1_16b_f32 v[72:75], v126, v38, v[72:75]
	s_nop 1
	v_mfma_f32_4x4x1_16b_f32 v[72:75], v127, v39, v[72:75]
	s_nop 1
	v_mfma_f32_4x4x1_16b_f32 v[72:75], v128, v40, v[72:75]
	s_nop 1
	v_mfma_f32_4x4x1_16b_f32 v[72:75], v129, v41, v[72:75]
	s_nop 1
	v_mfma_f32_4x4x1_16b_f32 v[72:75], v130, v42, v[72:75]
	s_nop 1
	v_mfma_f32_4x4x1_16b_f32 v[72:75], v131, v43, v[72:75]
	s_nop 1
	v_mfma_f32_4x4x1_16b_f32 v[72:75], v132, v44, v[72:75]
	s_nop 1
	v_mfma_f32_4x4x1_16b_f32 v[72:75], v133, v45, v[72:75]
	s_nop 1
	v_mfma_f32_4x4x1_16b_f32 v[72:75], v134, v46, v[72:75]
	s_nop 1
	v_mfma_f32_4x4x1_16b_f32 v[72:75], v135, v47, v[72:75]
	s_nop 1
	ds_read_b128 v[120:123], v234 offset:14208
	ds_read_b128 v[124:127], v234 offset:14224
	ds_read_b128 v[128:131], v234 offset:14240
	ds_read_b128 v[132:135], v234 offset:14256
	s_waitcnt lgkmcnt(8)
	s_nop 3
	v_mov_b32_e32 v235, v72
	s_nop 1
	v_mfma_f32_4x4x1_16b_f32 v[72:75], v88, v235, v[72:75]
	s_nop 1
	s_nop 3
	v_mov_b32_e32 v235, v73
	s_nop 1
	v_mfma_f32_4x4x1_16b_f32 v[72:75], v89, v235, v[72:75]
	s_nop 1
	s_nop 3
	v_mov_b32_e32 v235, v74
	s_nop 1
	v_mfma_f32_4x4x1_16b_f32 v[72:75], v90, v235, v[72:75]
	s_nop 1
	ds_read_b128 v[88:91], v234 offset:14272
	ds_read_b128 v[92:95], v234 offset:14288
	ds_read_b128 v[96:99], v234 offset:14304
	ds_read_b128 v[100:103], v234 offset:14320
	s_waitcnt lgkmcnt(8)
	s_nop 4
	v_mfma_f32_4x4x1_16b_f32 v[76:79], v104, v0, v[76:79]
	s_nop 1
	v_mfma_f32_4x4x1_16b_f32 v[76:79], v105, v1, v[76:79]
	s_nop 1
	v_mfma_f32_4x4x1_16b_f32 v[76:79], v106, v2, v[76:79]
	s_nop 1
	v_mfma_f32_4x4x1_16b_f32 v[76:79], v107, v3, v[76:79]
	s_nop 1
	v_mfma_f32_4x4x1_16b_f32 v[76:79], v108, v4, v[76:79]
	s_nop 1
	v_mfma_f32_4x4x1_16b_f32 v[76:79], v109, v5, v[76:79]
	s_nop 1
	v_mfma_f32_4x4x1_16b_f32 v[76:79], v110, v6, v[76:79]
	s_nop 1
	v_mfma_f32_4x4x1_16b_f32 v[76:79], v111, v7, v[76:79]
	s_nop 1
	v_mfma_f32_4x4x1_16b_f32 v[76:79], v112, v8, v[76:79]
	s_nop 1
	v_mfma_f32_4x4x1_16b_f32 v[76:79], v113, v9, v[76:79]
	s_nop 1
	v_mfma_f32_4x4x1_16b_f32 v[76:79], v114, v10, v[76:79]
	s_nop 1
	v_mfma_f32_4x4x1_16b_f32 v[76:79], v115, v11, v[76:79]
	s_nop 1
	v_mfma_f32_4x4x1_16b_f32 v[76:79], v116, v12, v[76:79]
	s_nop 1
	v_mfma_f32_4x4x1_16b_f32 v[76:79], v117, v13, v[76:79]
	s_nop 1
	v_mfma_f32_4x4x1_16b_f32 v[76:79], v118, v14, v[76:79]
	s_nop 1
	v_mfma_f32_4x4x1_16b_f32 v[76:79], v119, v15, v[76:79]
	s_nop 1
	ds_read_b128 v[104:107], v234 offset:14336
	ds_read_b128 v[108:111], v234 offset:14352
	s_waitcnt lgkmcnt(6)
	v_mfma_f32_4x4x1_16b_f32 v[76:79], v120, v16, v[76:79]
	s_nop 1
	v_mfma_f32_4x4x1_16b_f32 v[76:79], v121, v17, v[76:79]
	s_nop 1
	v_mfma_f32_4x4x1_16b_f32 v[76:79], v122, v18, v[76:79]
	s_nop 1
	v_mfma_f32_4x4x1_16b_f32 v[76:79], v123, v19, v[76:79]
	s_nop 1
	v_mfma_f32_4x4x1_16b_f32 v[76:79], v124, v20, v[76:79]
	s_nop 1
	v_mfma_f32_4x4x1_16b_f32 v[76:79], v125, v21, v[76:79]
	s_nop 1
	v_mfma_f32_4x4x1_16b_f32 v[76:79], v126, v22, v[76:79]
	s_nop 1
	v_mfma_f32_4x4x1_16b_f32 v[76:79], v127, v23, v[76:79]
	s_nop 1
	v_mfma_f32_4x4x1_16b_f32 v[76:79], v128, v24, v[76:79]
	s_nop 1
	v_mfma_f32_4x4x1_16b_f32 v[76:79], v129, v25, v[76:79]
	s_nop 1
	v_mfma_f32_4x4x1_16b_f32 v[76:79], v130, v26, v[76:79]
	s_nop 1
	v_mfma_f32_4x4x1_16b_f32 v[76:79], v131, v27, v[76:79]
	s_nop 1
	v_mfma_f32_4x4x1_16b_f32 v[76:79], v132, v28, v[76:79]
	s_nop 1
	v_mfma_f32_4x4x1_16b_f32 v[76:79], v133, v29, v[76:79]
	s_nop 1
	v_mfma_f32_4x4x1_16b_f32 v[76:79], v134, v30, v[76:79]
	s_nop 1
	v_mfma_f32_4x4x1_16b_f32 v[76:79], v135, v31, v[76:79]
	s_nop 1
	ds_read_b128 v[120:123], v234 offset:15232
	ds_read_b128 v[124:127], v234 offset:15248
	ds_read_b128 v[128:131], v234 offset:15264
	ds_read_b128 v[132:135], v234 offset:15280
	s_waitcnt lgkmcnt(6)
	v_mfma_f32_4x4x1_16b_f32 v[76:79], v88, v32, v[76:79]
	s_nop 1
	v_mfma_f32_4x4x1_16b_f32 v[76:79], v89, v33, v[76:79]
	s_nop 1
	v_mfma_f32_4x4x1_16b_f32 v[76:79], v90, v34, v[76:79]
	s_nop 1
	v_mfma_f32_4x4x1_16b_f32 v[76:79], v91, v35, v[76:79]
	s_nop 1
	v_mfma_f32_4x4x1_16b_f32 v[76:79], v92, v36, v[76:79]
	s_nop 1
	v_mfma_f32_4x4x1_16b_f32 v[76:79], v93, v37, v[76:79]
	s_nop 1
	v_mfma_f32_4x4x1_16b_f32 v[76:79], v94, v38, v[76:79]
	s_nop 1
	v_mfma_f32_4x4x1_16b_f32 v[76:79], v95, v39, v[76:79]
	s_nop 1
	v_mfma_f32_4x4x1_16b_f32 v[76:79], v96, v40, v[76:79]
	s_nop 1
	v_mfma_f32_4x4x1_16b_f32 v[76:79], v97, v41, v[76:79]
	s_nop 1
	v_mfma_f32_4x4x1_16b_f32 v[76:79], v98, v42, v[76:79]
	s_nop 1
	v_mfma_f32_4x4x1_16b_f32 v[76:79], v99, v43, v[76:79]
	s_nop 1
	v_mfma_f32_4x4x1_16b_f32 v[76:79], v100, v44, v[76:79]
	s_nop 1
	v_mfma_f32_4x4x1_16b_f32 v[76:79], v101, v45, v[76:79]
	s_nop 1
	v_mfma_f32_4x4x1_16b_f32 v[76:79], v102, v46, v[76:79]
	s_nop 1
	v_mfma_f32_4x4x1_16b_f32 v[76:79], v103, v47, v[76:79]
	s_nop 1
	ds_read_b128 v[88:91], v234 offset:15296
	ds_read_b128 v[92:95], v234 offset:15312
	ds_read_b128 v[96:99], v234 offset:15328
	ds_read_b128 v[100:103], v234 offset:15344
	s_waitcnt lgkmcnt(8)
; #define LAS __attribute__((address_space(3)))
; __device__ __forceinline__ void dn_prep_item(const Args& a, LAS unsigned char* lds, int item, int tid, int wave, int lane, int& cwh, int next_item) {
;     ...
;         { const LAS float* lrow = Lm + (lane & 15);
; #pragma unroll
;         for (int i = 1; i < 64; ++i) { float sa[4] = { x[i], 0.f, 0.f, 0.f };
;             int lr[4];
; #pragma unroll
;             for (int g = 0; g < (i + 15) / 16; ++g) lr[g] = __float_as_int(lrow[i * 68 + 16 * g]);
; #pragma unroll
;             for (int j = 0; j < i; ++j) { fmac_rowbcast_sel(sa[j & 3], lr[j >> 4], x[j], j); }
;             x[i] = (sa[0] + sa[1]) + (sa[2] + sa[3]); } }
	v_mfma_f32_4x4x1_16b_f32 v[76:79], v104, v72, v[76:79]
	s_nop 1
	v_mfma_f32_4x4x1_16b_f32 v[76:79], v105, v73, v[76:79]
	s_nop 1
	v_mfma_f32_4x4x1_16b_f32 v[76:79], v106, v74, v[76:79]
	s_nop 1
	v_mfma_f32_4x4x1_16b_f32 v[76:79], v107, v75, v[76:79]
	s_nop 1
	s_nop 3
	v_mov_b32_e32 v235, v76
	s_nop 1
	v_mfma_f32_4x4x1_16b_f32 v[76:79], v108, v235, v[76:79]
	s_nop 1
	s_nop 3
	v_mov_b32_e32 v235, v77
	s_nop 1
	v_mfma_f32_4x4x1_16b_f32 v[76:79], v109, v235, v[76:79]
	s_nop 1
	s_nop 3
	v_mov_b32_e32 v235, v78
	s_nop 1
	v_mfma_f32_4x4x1_16b_f32 v[76:79], v110, v235, v[76:79]
	s_nop 1
	ds_read_b128 v[104:107], v234 offset:15360
	ds_read_b128 v[108:111], v234 offset:15376
	ds_read_b128 v[112:115], v234 offset:15392
	ds_read_b128 v[116:119], v234 offset:15408
	s_waitcnt lgkmcnt(8)
	s_nop 4
	v_mfma_f32_4x4x1_16b_f32 v[80:83], v120, v0, v[80:83]
	s_nop 1
	v_mfma_f32_4x4x1_16b_f32 v[80:83], v121, v1, v[80:83]
	s_nop 1
	v_mfma_f32_4x4x1_16b_f32 v[80:83], v122, v2, v[80:83]
	s_nop 1
	v_mfma_f32_4x4x1_16b_f32 v[80:83], v123, v3, v[80:83]
	s_nop 1
	v_mfma_f32_4x4x1_16b_f32 v[80:83], v124, v4, v[80:83]
	s_nop 1
	v_mfma_f32_4x4x1_16b_f32 v[80:83], v125, v5, v[80:83]
	s_nop 1
	v_mfma_f32_4x4x1_16b_f32 v[80:83], v126, v6, v[80:83]
	s_nop 1
	v_mfma_f32_4x4x1_16b_f32 v[80:83], v127, v7, v[80:83]
	s_nop 1
	v_mfma_f32_4x4x1_16b_f32 v[80:83], v128, v8, v[80:83]
	s_nop 1
	v_mfma_f32_4x4x1_16b_f32 v[80:83], v129, v9, v[80:83]
	s_nop 1
	v_mfma_f32_4x4x1_16b_f32 v[80:83], v130, v10, v[80:83]
	s_nop 1
	v_mfma_f32_4x4x1_16b_f32 v[80:83], v131, v11, v[80:83]
	s_nop 1
	v_mfma_f32_4x4x1_16b_f32 v[80:83], v132, v12, v[80:83]
	s_nop 1
	v_mfma_f32_4x4x1_16b_f32 v[80:83], v133, v13, v[80:83]
	s_nop 1
	v_mfma_f32_4x4x1_16b_f32 v[80:83], v134, v14, v[80:83]
	s_nop 1
	v_mfma_f32_4x4x1_16b_f32 v[80:83], v135, v15, v[80:83]
	s_nop 1
	ds_read_b128 v[120:123], v234 offset:15424
	ds_read_b128 v[124:127], v234 offset:15440
	ds_read_b128 v[128:131], v234 offset:15456
	s_waitcnt lgkmcnt(7)
	v_mfma_f32_4x4x1_16b_f32 v[80:83], v88, v16, v[80:83]
	s_nop 1
	v_mfma_f32_4x4x1_16b_f32 v[80:83], v89, v17, v[80:83]
	s_nop 1
	v_mfma_f32_4x4x1_16b_f32 v[80:83], v90, v18, v[80:83]
	s_nop 1
	v_mfma_f32_4x4x1_16b_f32 v[80:83], v91, v19, v[80:83]
	s_nop 1
	v_mfma_f32_4x4x1_16b_f32 v[80:83], v92, v20, v[80:83]
	s_nop 1
	v_mfma_f32_4x4x1_16b_f32 v[80:83], v93, v21, v[80:83]
	s_nop 1
	v_mfma_f32_4x4x1_16b_f32 v[80:83], v94, v22, v[80:83]
	s_nop 1
	v_mfma_f32_4x4x1_16b_f32 v[80:83], v95, v23, v[80:83]
	s_nop 1
	v_mfma_f32_4x4x1_16b_f32 v[80:83], v96, v24, v[80:83]
	s_nop 1
	v_mfma_f32_4x4x1_16b_f32 v[80:83], v97, v25, v[80:83]
	s_nop 1
	v_mfma_f32_4x4x1_16b_f32 v[80:83], v98, v26, v[80:83]
	s_nop 1
	v_mfma_f32_4x4x1_16b_f32 v[80:83], v99, v27, v[80:83]
	s_nop 1
	v_mfma_f32_4x4x1_16b_f32 v[80:83], v100, v28, v[80:83]
	s_nop 1
	v_mfma_f32_4x4x1_16b_f32 v[80:83], v101, v29, v[80:83]
	s_nop 1
	v_mfma_f32_4x4x1_16b_f32 v[80:83], v102, v30, v[80:83]
	s_nop 1
	v_mfma_f32_4x4x1_16b_f32 v[80:83], v103, v31, v[80:83]
	s_nop 1
	ds_read_b128 v[88:91], v234 offset:16320
	ds_read_b128 v[92:95], v234 offset:16336
	ds_read_b128 v[96:99], v234 offset:16352
	ds_read_b128 v[100:103], v234 offset:16368
	s_waitcnt lgkmcnt(7)
	v_mfma_f32_4x4x1_16b_f32 v[80:83], v104, v32, v[80:83]
	s_nop 1
	v_mfma_f32_4x4x1_16b_f32 v[80:83], v105, v33, v[80:83]
	s_nop 1
	v_mfma_f32_4x4x1_16b_f32 v[80:83], v106, v34, v[80:83]
	s_nop 1
	v_mfma_f32_4x4x1_16b_f32 v[80:83], v107, v35, v[80:83]
	s_nop 1
	v_mfma_f32_4x4x1_16b_f32 v[80:83], v108, v36, v[80:83]
	s_nop 1
	v_mfma_f32_4x4x1_16b_f32 v[80:83], v109, v37, v[80:83]
	s_nop 1
	v_mfma_f32_4x4x1_16b_f32 v[80:83], v110, v38, v[80:83]
	s_nop 1
	v_mfma_f32_4x4x1_16b_f32 v[80:83], v111, v39, v[80:83]
	s_nop 1
	v_mfma_f32_4x4x1_16b_f32 v[80:83], v112, v40, v[80:83]
	s_nop 1
	v_mfma_f32_4x4x1_16b_f32 v[80:83], v113, v41, v[80:83]
	s_nop 1
	v_mfma_f32_4x4x1_16b_f32 v[80:83], v114, v42, v[80:83]
	s_nop 1
	v_mfma_f32_4x4x1_16b_f32 v[80:83], v115, v43, v[80:83]
	s_nop 1
	v_mfma_f32_4x4x1_16b_f32 v[80:83], v116, v44, v[80:83]
	s_nop 1
	v_mfma_f32_4x4x1_16b_f32 v[80:83], v117, v45, v[80:83]
	s_nop 1
	v_mfma_f32_4x4x1_16b_f32 v[80:83], v118, v46, v[80:83]
	s_nop 1
	v_mfma_f32_4x4x1_16b_f32 v[80:83], v119, v47, v[80:83]
	s_nop 1
	ds_read_b128 v[104:107], v234 offset:16384
	ds_read_b128 v[108:111], v234 offset:16400
	ds_read_b128 v[112:115], v234 offset:16416
	ds_read_b128 v[116:119], v234 offset:16432
	s_waitcnt lgkmcnt(8)
	v_mfma_f32_4x4x1_16b_f32 v[80:83], v120, v72, v[80:83]
	s_nop 1
	v_mfma_f32_4x4x1_16b_f32 v[80:83], v121, v73, v[80:83]
	s_nop 1
	v_mfma_f32_4x4x1_16b_f32 v[80:83], v122, v74, v[80:83]
	s_nop 1
	v_mfma_f32_4x4x1_16b_f32 v[80:83], v123, v75, v[80:83]
	s_nop 1
	v_mfma_f32_4x4x1_16b_f32 v[80:83], v124, v76, v[80:83]
	s_nop 1
	v_mfma_f32_4x4x1_16b_f32 v[80:83], v125, v77, v[80:83]
	s_nop 1
	v_mfma_f32_4x4x1_16b_f32 v[80:83], v126, v78, v[80:83]
	s_nop 1
	v_mfma_f32_4x4x1_16b_f32 v[80:83], v127, v79, v[80:83]
	s_nop 1
	s_nop 3
	v_mov_b32_e32 v235, v80
	s_nop 1
	v_mfma_f32_4x4x1_16b_f32 v[80:83], v128, v235, v[80:83]
	s_nop 1
	s_nop 3
	v_mov_b32_e32 v235, v81
	s_nop 1
	v_mfma_f32_4x4x1_16b_f32 v[80:83], v129, v235, v[80:83]
	s_nop 1
	s_nop 3
	v_mov_b32_e32 v235, v82
	s_nop 1
	v_mfma_f32_4x4x1_16b_f32 v[80:83], v130, v235, v[80:83]
	s_nop 1
	ds_read_b128 v[120:123], v234 offset:16448
	ds_read_b128 v[124:127], v234 offset:16464
	ds_read_b128 v[128:131], v234 offset:16480
	ds_read_b128 v[132:135], v234 offset:16496
	s_waitcnt lgkmcnt(8)
; #define LAS __attribute__((address_space(3)))
; __device__ __forceinline__ unsigned pk2(float lo, float hi) { const f32x2_t v = {lo, hi}; const bf16x2_t b = __builtin_convertvector(v, bf16x2_t); return __builtin_bit_cast(unsigned, b); }
; __device__ __forceinline__ void dn_prep_item(const Args& a, LAS unsigned char* lds, int item, int tid, int wave, int lane, int& cwh, int next_item) {
;     ...
;         for (int i = 1; i < 64; ++i) { float sa[4] = { x[i], 0.f, 0.f, 0.f };
;             int lr[4];
; #pragma unroll
;             for (int g = 0; g < (i + 15) / 16; ++g) lr[g] = __float_as_int(lrow[i * 68 + 16 * g]);
; #pragma unroll
;             for (int j = 0; j < i; ++j) { fmac_rowbcast_sel(sa[j & 3], lr[j >> 4], x[j], j); }
;             x[i] = (sa[0] + sa[1]) + (sa[2] + sa[3]); } }
; #pragma unroll
;         for (int q = 0; q < 8; ++q) { v4u w; w.x = pk2(x[8 * q], x[8 * q + 1]); w.y = pk2(x[8 * q + 2], x[8 * q + 3]); w.z = pk2(x[8 * q + 4], x[8 * q + 5]); w.w = pk2(x[8 * q + 6], x[8 * q + 7]);
;             *(LAS v4u*)(lds + L_SOL + tid * AS_ + 16 * q) = w; }
	s_nop 4
	v_mfma_f32_4x4x1_16b_f32 v[84:87], v88, v0, v[84:87]
	s_nop 1
	v_mfma_f32_4x4x1_16b_f32 v[84:87], v89, v1, v[84:87]
	s_nop 1
	v_mfma_f32_4x4x1_16b_f32 v[84:87], v90, v2, v[84:87]
	s_nop 1
	v_mfma_f32_4x4x1_16b_f32 v[84:87], v91, v3, v[84:87]
	s_nop 1
	v_mfma_f32_4x4x1_16b_f32 v[84:87], v92, v4, v[84:87]
	s_nop 1
	v_mfma_f32_4x4x1_16b_f32 v[84:87], v93, v5, v[84:87]
	s_nop 1
	v_mfma_f32_4x4x1_16b_f32 v[84:87], v94, v6, v[84:87]
	s_nop 1
	v_mfma_f32_4x4x1_16b_f32 v[84:87], v95, v7, v[84:87]
	s_nop 1
	v_mfma_f32_4x4x1_16b_f32 v[84:87], v96, v8, v[84:87]
	s_nop 1
	v_mfma_f32_4x4x1_16b_f32 v[84:87], v97, v9, v[84:87]
	s_nop 1
	v_mfma_f32_4x4x1_16b_f32 v[84:87], v98, v10, v[84:87]
	s_nop 1
	v_mfma_f32_4x4x1_16b_f32 v[84:87], v99, v11, v[84:87]
	s_nop 1
	v_mfma_f32_4x4x1_16b_f32 v[84:87], v100, v12, v[84:87]
	s_nop 1
	v_mfma_f32_4x4x1_16b_f32 v[84:87], v101, v13, v[84:87]
	s_nop 1
	v_mfma_f32_4x4x1_16b_f32 v[84:87], v102, v14, v[84:87]
	s_nop 1
	v_mfma_f32_4x4x1_16b_f32 v[84:87], v103, v15, v[84:87]
	s_nop 1
	ds_read_b128 v[88:91], v234 offset:16512
	ds_read_b128 v[92:95], v234 offset:16528
	ds_read_b128 v[96:99], v234 offset:16544
	ds_read_b128 v[100:103], v234 offset:16560
	s_waitcnt lgkmcnt(8)
	v_mfma_f32_4x4x1_16b_f32 v[84:87], v104, v16, v[84:87]
	s_nop 1
	v_mfma_f32_4x4x1_16b_f32 v[84:87], v105, v17, v[84:87]
	s_nop 1
	v_mfma_f32_4x4x1_16b_f32 v[84:87], v106, v18, v[84:87]
	s_nop 1
	v_mfma_f32_4x4x1_16b_f32 v[84:87], v107, v19, v[84:87]
	s_nop 1
	v_mfma_f32_4x4x1_16b_f32 v[84:87], v108, v20, v[84:87]
	s_nop 1
	v_mfma_f32_4x4x1_16b_f32 v[84:87], v109, v21, v[84:87]
	s_nop 1
	v_mfma_f32_4x4x1_16b_f32 v[84:87], v110, v22, v[84:87]
	s_nop 1
	v_mfma_f32_4x4x1_16b_f32 v[84:87], v111, v23, v[84:87]
	s_nop 1
	v_mfma_f32_4x4x1_16b_f32 v[84:87], v112, v24, v[84:87]
	s_nop 1
	v_mfma_f32_4x4x1_16b_f32 v[84:87], v113, v25, v[84:87]
	s_nop 1
	v_mfma_f32_4x4x1_16b_f32 v[84:87], v114, v26, v[84:87]
	s_nop 1
	v_mfma_f32_4x4x1_16b_f32 v[84:87], v115, v27, v[84:87]
	s_nop 1
	v_mfma_f32_4x4x1_16b_f32 v[84:87], v116, v28, v[84:87]
	s_nop 1
	v_mfma_f32_4x4x1_16b_f32 v[84:87], v117, v29, v[84:87]
	s_nop 1
	v_mfma_f32_4x4x1_16b_f32 v[84:87], v118, v30, v[84:87]
	s_nop 1
	v_mfma_f32_4x4x1_16b_f32 v[84:87], v119, v31, v[84:87]
	s_nop 1
	s_waitcnt lgkmcnt(4)
	v_mfma_f32_4x4x1_16b_f32 v[84:87], v120, v32, v[84:87]
	s_nop 1
	v_mfma_f32_4x4x1_16b_f32 v[84:87], v121, v33, v[84:87]
	s_nop 1
	v_mfma_f32_4x4x1_16b_f32 v[84:87], v122, v34, v[84:87]
	s_nop 1
	v_mfma_f32_4x4x1_16b_f32 v[84:87], v123, v35, v[84:87]
	s_nop 1
	v_mfma_f32_4x4x1_16b_f32 v[84:87], v124, v36, v[84:87]
	s_nop 1
	v_mfma_f32_4x4x1_16b_f32 v[84:87], v125, v37, v[84:87]
	s_nop 1
	v_mfma_f32_4x4x1_16b_f32 v[84:87], v126, v38, v[84:87]
	s_nop 1
	v_mfma_f32_4x4x1_16b_f32 v[84:87], v127, v39, v[84:87]
	s_nop 1
	v_mfma_f32_4x4x1_16b_f32 v[84:87], v128, v40, v[84:87]
	s_nop 1
	v_mfma_f32_4x4x1_16b_f32 v[84:87], v129, v41, v[84:87]
	s_nop 1
	v_mfma_f32_4x4x1_16b_f32 v[84:87], v130, v42, v[84:87]
	s_nop 1
	v_mfma_f32_4x4x1_16b_f32 v[84:87], v131, v43, v[84:87]
	s_nop 1
	v_mfma_f32_4x4x1_16b_f32 v[84:87], v132, v44, v[84:87]
	s_nop 1
	v_mfma_f32_4x4x1_16b_f32 v[84:87], v133, v45, v[84:87]
	s_nop 1
	v_mfma_f32_4x4x1_16b_f32 v[84:87], v134, v46, v[84:87]
	s_nop 1
	v_mfma_f32_4x4x1_16b_f32 v[84:87], v135, v47, v[84:87]
	s_nop 1
	s_waitcnt lgkmcnt(0)
	v_mfma_f32_4x4x1_16b_f32 v[84:87], v88, v72, v[84:87]
	s_nop 1
	v_mfma_f32_4x4x1_16b_f32 v[84:87], v89, v73, v[84:87]
	s_nop 1
	v_mfma_f32_4x4x1_16b_f32 v[84:87], v90, v74, v[84:87]
	s_nop 1
	v_mfma_f32_4x4x1_16b_f32 v[84:87], v91, v75, v[84:87]
	s_nop 1
	v_mfma_f32_4x4x1_16b_f32 v[84:87], v92, v76, v[84:87]
	s_nop 1
	v_mfma_f32_4x4x1_16b_f32 v[84:87], v93, v77, v[84:87]
	s_nop 1
	v_mfma_f32_4x4x1_16b_f32 v[84:87], v94, v78, v[84:87]
	s_nop 1
	v_mfma_f32_4x4x1_16b_f32 v[84:87], v95, v79, v[84:87]
	s_nop 1
	v_mfma_f32_4x4x1_16b_f32 v[84:87], v96, v80, v[84:87]
	s_nop 1
	v_mfma_f32_4x4x1_16b_f32 v[84:87], v97, v81, v[84:87]
	s_nop 1
	v_mfma_f32_4x4x1_16b_f32 v[84:87], v98, v82, v[84:87]
	s_nop 1
	v_mfma_f32_4x4x1_16b_f32 v[84:87], v99, v83, v[84:87]
	s_nop 1
	s_nop 3
	v_mov_b32_e32 v235, v84
	s_nop 1
	v_mfma_f32_4x4x1_16b_f32 v[84:87], v100, v235, v[84:87]
	s_nop 1
	s_nop 3
	v_mov_b32_e32 v235, v85
	s_nop 1
	v_mfma_f32_4x4x1_16b_f32 v[84:87], v101, v235, v[84:87]
	s_nop 1
	s_nop 3
	v_mov_b32_e32 v235, v86
	s_nop 1
	v_mfma_f32_4x4x1_16b_f32 v[84:87], v102, v235, v[84:87]
	s_nop 1
	s_nop 4
	v_cvt_pk_bf16_f32 v236, v0, v1
	v_cvt_pk_bf16_f32 v237, v2, v3
	v_cvt_pk_bf16_f32 v238, v4, v5
	v_cvt_pk_bf16_f32 v239, v6, v7
	ds_write_b128 v223, v[236:239] offset:61440
	v_cvt_pk_bf16_f32 v236, v8, v9
	v_cvt_pk_bf16_f32 v237, v10, v11
	v_cvt_pk_bf16_f32 v238, v12, v13
	v_cvt_pk_bf16_f32 v239, v14, v15
	ds_write_b128 v223, v[236:239] offset:61456
	v_cvt_pk_bf16_f32 v236, v16, v17
	v_cvt_pk_bf16_f32 v237, v18, v19
	v_cvt_pk_bf16_f32 v238, v20, v21
	v_cvt_pk_bf16_f32 v239, v22, v23
	ds_write_b128 v223, v[236:239] offset:61472
	v_cvt_pk_bf16_f32 v236, v24, v25
	v_cvt_pk_bf16_f32 v237, v26, v27
	v_cvt_pk_bf16_f32 v238, v28, v29
	v_cvt_pk_bf16_f32 v239, v30, v31
	ds_write_b128 v223, v[236:239] offset:61488
	v_cvt_pk_bf16_f32 v236, v32, v33
	v_cvt_pk_bf16_f32 v237, v34, v35
	v_cvt_pk_bf16_f32 v238, v36, v37
	v_cvt_pk_bf16_f32 v239, v38, v39
	ds_write_b128 v223, v[236:239] offset:61504
	v_cvt_pk_bf16_f32 v236, v40, v41
	v_cvt_pk_bf16_f32 v237, v42, v43
	v_cvt_pk_bf16_f32 v238, v44, v45
	v_cvt_pk_bf16_f32 v239, v46, v47
	ds_write_b128 v223, v[236:239] offset:61520
	v_cvt_pk_bf16_f32 v236, v72, v73
	v_cvt_pk_bf16_f32 v237, v74, v75
	v_cvt_pk_bf16_f32 v238, v76, v77
	v_cvt_pk_bf16_f32 v239, v78, v79
	ds_write_b128 v223, v[236:239] offset:61536
	v_cvt_pk_bf16_f32 v236, v80, v81
	v_cvt_pk_bf16_f32 v237, v82, v83
	v_cvt_pk_bf16_f32 v238, v84, v85
	v_cvt_pk_bf16_f32 v239, v86, v87
	ds_write_b128 v223, v[236:239] offset:61552
